# HGRN2 scan: the eight per-chunk load addresses come from four per-unit base registers plus signed immediate offsets (29 fewer instructions per chunk)
# baseline (speedup 1.0000x reference)
.LBB0_417:
	s_or_b64 exec, exec, s[40:41]
	v_and_b32_e32 v30, 63, v8
	s_waitcnt vmcnt(0)
	v_and_b32_e32 v54, 0xffff, v14
	v_lshrrev_b32_e32 v14, 5, v30
	v_and_b32_e32 v53, 0xffff, v16
	v_lshlrev_b32_e32 v52, 2, v14
	v_lshrrev_b32_e32 v16, 2, v12
	v_and_b32_e32 v0, 0xffff, v15
	v_lshlrev_b32_e32 v2, 5, v10
	v_lshlrev_b32_e32 v15, 3, v8
	v_or_b32_e32 v16, v52, v16
	v_and_b32_e32 v3, 24, v15
	v_lshlrev_b32_e32 v16, 6, v16
	v_and_b32_e32 v2, 32, v2
	v_or3_b32 v16, v3, v2, v16
	v_lshl_add_u64 v[2:3], v[6:7], 1, s[4:5]
	v_lshl_add_u64 v[2:3], v[2:3], 0, s[8:9]
	s_lshl_b32 s8, s42, 1
	v_lshlrev_b32_e32 v6, 2, v13
	v_lshl_add_u64 v[2:3], v[2:3], 0, s[8:9]
	v_ashrrev_i32_e32 v7, 31, v6
	v_lshl_add_u64 v[38:39], v[6:7], 1, v[2:3]
	v_and_or_b32 v2, v246, 64, v12
	v_lshlrev_b32_e32 v55, 2, v2
	v_lshl_add_u32 v2, v4, 6, 0
	v_cmp_eq_u32_e64 s[44:45], 3, v10
	v_lshlrev_b32_e32 v3, 1, v11
	v_lshl_add_u32 v6, v4, 4, v2
	s_movk_i32 s47, 0xffb4
	v_and_b32_e32 v10, 0xfffff800, v15
	v_add_u32_e32 v60, v2, v3
	v_add_u32_e32 v61, v6, v3
	v_lshlrev_b32_e32 v3, 2, v48
	v_mul_lo_u32 v7, v4, s47
	v_add_u32_e32 v10, 0, v10
	v_lshlrev_b32_e32 v11, 8, v9
	s_lshl_b32 s47, s25, 5
	s_lshl_b32 s25, s25, 11
	s_ashr_i32 s46, s24, 7
	v_add3_u32 v62, v10, v11, v3
	v_and_or_b32 v10, s47, 32, v48
	s_add_i32 s25, s25, 0
	v_mul_u32_u24_e32 v64, 0x50, v10
	v_add_u32_e32 v10, s25, v3
	v_lshl_or_b32 v3, s46, 5, v48
	s_movk_i32 s25, 0x50
	v_mul_lo_u32 v3, v3, s25
	v_lshlrev_b32_e32 v11, 4, v14
	v_add_u32_e32 v2, 0, v16
	s_lshl_b32 s47, s46, 11
	v_add3_u32 v66, 0, v3, v11
	v_or_b32_e32 v3, 3, v52
	s_lshl_b32 s6, s36, 1
	v_and_b32_e32 v41, 0xffff, v17
	s_and_b32 s24, s24, 0xffffff80
	v_add_u32_e32 v68, s47, v2
	v_or_b32_e32 v2, 2, v52
	v_cmp_gt_u32_e64 s[52:53], v3, v48
	v_or_b32_e32 v3, 8, v52
	v_or_b32_e32 v17, 27, v52
	s_lshl_b64 s[0:1], s[0:1], 23
	s_and_b32 s7, s6, 0x700
	v_and_b32_e32 v40, 0xffff, v18
	s_add_i32 s24, s24, 0
	v_cmp_gt_u32_e64 s[50:51], v2, v48
	v_cmp_gt_u32_e64 s[54:55], v3, v48
	v_cmp_gt_u32_e64 s[76:77], v17, v48
	v_lshlrev_b32_e32 v17, 6, v2
	v_lshlrev_b32_e32 v18, 6, v3
	v_lshl_or_b32 v2, v48, 11, s0
	v_lshrrev_b32_e32 v3, 1, v8
	s_and_b32 s6, s6, 0x80
	v_add_u32_e32 v71, s24, v11
	v_or_b32_e32 v2, s7, v2
	v_and_b32_e32 v3, 0x70, v3
	v_readlane_b32 s24, v254, 44
	v_or3_b32 v2, v2, s6, v3
	v_mov_b32_e32 v3, s1
	v_readlane_b32 s25, v254, 45
	v_mul_u32_u24_e32 v67, 0x280, v9
	v_or_b32_e32 v9, 9, v52
	v_lshl_add_u64 v[46:47], s[24:25], 0, v[2:3]
	v_and_b32_e32 v2, 48, v8
	v_lshl_or_b32 v2, v2, 10, s0
	v_or_b32_e32 v12, 11, v52
	v_or_b32_e32 v13, 17, v52
	v_or_b32_e32 v15, 19, v52
	v_or_b32_e32 v16, 25, v52
	v_or_b32_e32 v2, s7, v2
	v_cmp_gt_u32_e64 s[56:57], v9, v48
	v_or_b32_e32 v9, 10, v52
	v_cmp_gt_u32_e64 s[60:61], v12, v48
	v_or_b32_e32 v12, 16, v52
	v_cmp_gt_u32_e64 s[64:65], v13, v48
	v_or_b32_e32 v13, 18, v52
	v_cmp_gt_u32_e64 s[68:69], v15, v48
	v_or_b32_e32 v15, 24, v52
	v_cmp_gt_u32_e64 s[72:73], v16, v48
	v_or_b32_e32 v16, 26, v52
	v_lshl_add_u64 v[2:3], v[4:5], 1, v[2:3]
	v_lshlrev_b32_e32 v65, 3, v14
	v_cmp_gt_u32_e64 s[58:59], v9, v48
	v_cmp_gt_u32_e64 s[62:63], v12, v48
	v_cmp_gt_u32_e64 s[66:67], v13, v48
	v_cmp_gt_u32_e64 s[70:71], v15, v48
	v_cmp_gt_u32_e64 s[74:75], v16, v48
	v_lshlrev_b32_e32 v14, 8, v14
	v_lshlrev_b32_e32 v9, 6, v9
	v_lshlrev_b32_e32 v12, 6, v12
	v_lshlrev_b32_e32 v13, 6, v13
	v_lshlrev_b32_e32 v15, 6, v15
	v_lshlrev_b32_e32 v16, 6, v16
	v_lshl_add_u64 v[50:51], s[18:19], 0, v[2:3]
	s_mov_b64 s[98:99], 0x10011000
	v_lshl_add_u64 v[196:197], v[50:51], 0, s[98:99]
	s_mov_b64 s[98:99], 0x18011000
	v_lshl_add_u64 v[198:199], v[50:51], 0, s[98:99]
	s_mov_b64 s[98:99], 0x10013000
	v_lshl_add_u64 v[200:201], v[50:51], 0, s[98:99]
	s_mov_b64 s[98:99], 0x18013000
	v_lshl_add_u64 v[202:203], v[50:51], 0, s[98:99]
	v_mov_b32_e32 v2, 0
	v_and_b32_e32 v59, 0xffff, v24
	v_and_b32_e32 v43, 0xffff, v25
	v_and_b32_e32 v63, 0xffff, v21
	v_and_b32_e32 v69, 0xffff, v22
	v_and_b32_e32 v45, 0xffff, v23
	v_and_b32_e32 v42, 0xffff, v20
	v_and_b32_e32 v70, 0xffff, v19
	v_and_b32_e32 v72, 0xffff, v27
	v_and_b32_e32 v49, 0xffff, v28
	v_and_b32_e32 v44, 0xffff, v26
	v_and_b32_e32 v73, 0xffff, v29
	s_mov_b32 s8, -1
	v_or_b32_e32 v56, 64, v55
	v_or_b32_e32 v57, 0x80, v55
	v_or_b32_e32 v58, 0xc0, v55
	v_cmp_gt_u32_e64 s[40:41], 16, v30
	v_cmp_lt_u32_e64 s[42:43], 31, v30
	v_cmp_gt_u32_e64 s[46:47], v52, v48
	v_cmp_lt_u32_e64 s[48:49], v52, v48
	s_mov_b64 s[0:1], 0
	v_add_u32_e32 v74, v6, v7
	v_add_u32_e32 v75, v10, v14
	v_add_u32_e32 v76, v10, v17
	v_add_u32_e32 v77, v10, v18
	v_add_u32_e32 v78, v10, v9
	v_add_u32_e32 v79, v10, v12
	v_add_u32_e32 v80, v10, v13
	v_add_u32_e32 v81, v10, v15
	v_add_u32_e32 v82, v10, v16
	v_mov_b32_e32 v3, v2
	v_mov_b32_e32 v4, v2
	v_mov_b32_e32 v5, v2
	v_mov_b32_e32 v6, v2
	v_mov_b32_e32 v7, v2
	v_mov_b32_e32 v8, v2
	v_mov_b32_e32 v9, v2
	v_mov_b32_e32 v10, v2
	v_mov_b32_e32 v11, v2
	v_mov_b32_e32 v12, v2
	v_mov_b32_e32 v13, v2
	v_mov_b32_e32 v14, v2
	v_mov_b32_e32 v15, v2
	v_mov_b32_e32 v16, v2
	v_mov_b32_e32 v17, v2
	s_branch .LBB0_419

.LBB0_425:
	v_lshl_add_u64 v[20:21], v[196:197], 0, s[0:1]
	v_lshl_add_u64 v[22:23], v[198:199], 0, s[0:1]
	v_lshl_add_u64 v[24:25], v[200:201], 0, s[0:1]
	v_lshl_add_u64 v[26:27], v[202:203], 0, s[0:1]
	global_load_ushort v0, v[20:21], off offset:-4096
	global_load_ushort v53, v[22:23], off offset:-4096
	global_load_ushort v54, v[22:23], off offset:-2048
	global_load_ushort v40, v[20:21], off
	global_load_ushort v59, v[22:23], off
	global_load_ushort v63, v[22:23], off offset:2048
	global_load_ushort v43, v[20:21], off offset:2048
	global_load_ushort v41, v[20:21], off offset:-2048
	global_load_ushort v42, v[24:25], off offset:-4096
	global_load_ushort v69, v[26:27], off offset:-4096
	global_load_ushort v70, v[26:27], off offset:-2048
	global_load_ushort v44, v[24:25], off
	global_load_ushort v72, v[26:27], off
	global_load_ushort v73, v[26:27], off offset:2048
	global_load_ushort v49, v[24:25], off offset:2048
	global_load_ushort v45, v[24:25], off offset:-2048
	s_and_saveexec_b64 vcc, s[38:39]
	s_cbranch_execz .LBB0_427
	v_lshl_add_u64 v[18:19], v[46:47], 0, s[0:1]
	global_load_dwordx4 v[34:37], v[18:19], off
